# attention: multi-iteration fast loop, hand-scheduled PV with V fragments prefetched 2 groups ahead, unit prologue loads batched, V ring mod 4; GEMM accumulator zeroing via v_mov_b64
# speedup vs baseline: 1.0187x; 1.0187x over previous
.LBB0_228:
	s_ashr_i32 s39, s38, 31
	s_lshl_b64 s[40:41], s[38:39], 19
	v_readlane_b32 s42, v238, 7
	v_readlane_b32 s43, v238, 8
	s_add_u32 s40, s42, s40
	s_addc_u32 s41, s43, s41
	s_and_b64 s[42:43], s[2:3], exec
	s_cselect_b32 s5, s41, s1
	s_cselect_b32 s7, s40, s0
	s_ashr_i32 s37, s36, 31
	s_lshl_b64 s[42:43], s[36:37], 19
	s_add_u32 s42, s64, s42
	s_addc_u32 s43, s65, s43
	s_and_b64 s[44:45], s[2:3], exec
	s_cselect_b32 s33, s43, s9
	s_cselect_b32 s37, s42, s8
	s_add_u32 s0, s0, 0x40080
	s_addc_u32 s1, s1, 0
	s_add_u32 s39, s8, 0x100
	s_addc_u32 s46, s9, 0
	s_mov_b32 s47, -2
	v_mov_b64_e32 v[0:1], 0
	v_mov_b64_e32 v[2:3], 0
	v_mov_b64_e32 v[4:5], 0
	v_mov_b64_e32 v[6:7], 0
	v_mov_b64_e32 v[8:9], 0
	v_mov_b64_e32 v[10:11], 0
	v_mov_b64_e32 v[12:13], 0
	v_mov_b64_e32 v[14:15], 0
	v_mov_b64_e32 v[16:17], 0
	v_mov_b64_e32 v[18:19], 0
	v_mov_b64_e32 v[20:21], 0
	v_mov_b64_e32 v[22:23], 0
	v_mov_b64_e32 v[24:25], 0
	v_mov_b64_e32 v[26:27], 0
	v_mov_b64_e32 v[28:29], 0
	v_mov_b64_e32 v[30:31], 0
	v_mov_b64_e32 v[32:33], 0
	v_mov_b64_e32 v[34:35], 0
	v_mov_b64_e32 v[36:37], 0
	v_mov_b64_e32 v[38:39], 0
	v_mov_b64_e32 v[40:41], 0
	v_mov_b64_e32 v[42:43], 0
	v_mov_b64_e32 v[44:45], 0
	v_mov_b64_e32 v[46:47], 0
	v_mov_b64_e32 v[48:49], 0
	v_mov_b64_e32 v[50:51], 0
	v_mov_b64_e32 v[52:53], 0
	v_mov_b64_e32 v[54:55], 0
	v_mov_b64_e32 v[56:57], 0
	v_mov_b64_e32 v[58:59], 0
	v_mov_b64_e32 v[60:61], 0
	v_mov_b64_e32 v[62:63], 0
	v_mov_b64_e32 v[64:65], 0
	v_mov_b64_e32 v[66:67], 0
	v_mov_b64_e32 v[68:69], 0
	v_mov_b64_e32 v[70:71], 0
	v_mov_b64_e32 v[72:73], 0
	v_mov_b64_e32 v[74:75], 0
	v_mov_b64_e32 v[76:77], 0
	v_mov_b64_e32 v[78:79], 0
	v_mov_b64_e32 v[80:81], 0
	v_mov_b64_e32 v[82:83], 0
	v_mov_b64_e32 v[84:85], 0
	v_mov_b64_e32 v[86:87], 0
	v_mov_b64_e32 v[88:89], 0
	v_mov_b64_e32 v[90:91], 0
	v_mov_b64_e32 v[92:93], 0
	v_mov_b64_e32 v[94:95], 0
	v_mov_b64_e32 v[96:97], 0
	v_mov_b64_e32 v[98:99], 0
	v_mov_b64_e32 v[100:101], 0
	v_mov_b64_e32 v[102:103], 0
	v_mov_b64_e32 v[104:105], 0
	v_mov_b64_e32 v[106:107], 0
	v_mov_b64_e32 v[108:109], 0
	v_mov_b64_e32 v[110:111], 0
	v_mov_b64_e32 v[112:113], 0
	v_mov_b64_e32 v[114:115], 0
	v_mov_b64_e32 v[116:117], 0
	v_mov_b64_e32 v[118:119], 0
	v_mov_b64_e32 v[120:121], 0
	v_mov_b64_e32 v[122:123], 0
	v_mov_b64_e32 v[124:125], 0
	v_mov_b64_e32 v[126:127], 0

.LBB0_550:
	s_add_u32 s59, s16, 0x100
	s_addc_u32 s60, s17, 0
	s_mov_b32 s61, -2
	s_waitcnt lgkmcnt(0)
	s_waitcnt vmcnt(0)
	v_mov_b64_e32 v[0:1], 0
	v_mov_b64_e32 v[2:3], 0
	v_mov_b64_e32 v[4:5], 0
	v_mov_b64_e32 v[6:7], 0
	v_mov_b64_e32 v[8:9], 0
	v_mov_b64_e32 v[10:11], 0
	v_mov_b64_e32 v[12:13], 0
	v_mov_b64_e32 v[14:15], 0
	v_mov_b64_e32 v[16:17], 0
	v_mov_b64_e32 v[18:19], 0
	v_mov_b64_e32 v[20:21], 0
	v_mov_b64_e32 v[22:23], 0
	v_mov_b64_e32 v[24:25], 0
	v_mov_b64_e32 v[26:27], 0
	v_mov_b64_e32 v[28:29], 0
	v_mov_b64_e32 v[30:31], 0
	v_mov_b64_e32 v[32:33], 0
	v_mov_b64_e32 v[34:35], 0
	v_mov_b64_e32 v[36:37], 0
	v_mov_b64_e32 v[38:39], 0
	v_mov_b64_e32 v[40:41], 0
	v_mov_b64_e32 v[42:43], 0
	v_mov_b64_e32 v[44:45], 0
	v_mov_b64_e32 v[46:47], 0
	v_mov_b64_e32 v[48:49], 0
	v_mov_b64_e32 v[50:51], 0
	v_mov_b64_e32 v[52:53], 0
	v_mov_b64_e32 v[54:55], 0
	v_mov_b64_e32 v[56:57], 0
	v_mov_b64_e32 v[58:59], 0
	v_mov_b64_e32 v[60:61], 0
	v_mov_b64_e32 v[62:63], 0
	v_mov_b64_e32 v[64:65], 0
	v_mov_b64_e32 v[66:67], 0
	v_mov_b64_e32 v[68:69], 0
	v_mov_b64_e32 v[70:71], 0
	v_mov_b64_e32 v[72:73], 0
	v_mov_b64_e32 v[74:75], 0
	v_mov_b64_e32 v[76:77], 0
	v_mov_b64_e32 v[78:79], 0
	v_mov_b64_e32 v[80:81], 0
	v_mov_b64_e32 v[82:83], 0
	v_mov_b64_e32 v[84:85], 0
	v_mov_b64_e32 v[86:87], 0
	v_mov_b64_e32 v[88:89], 0
	v_mov_b64_e32 v[90:91], 0
	v_mov_b64_e32 v[92:93], 0
	v_mov_b64_e32 v[94:95], 0
	v_mov_b64_e32 v[96:97], 0
	v_mov_b64_e32 v[98:99], 0
	v_mov_b64_e32 v[100:101], 0
	v_mov_b64_e32 v[102:103], 0
	v_mov_b64_e32 v[104:105], 0
	v_mov_b64_e32 v[106:107], 0
	v_mov_b64_e32 v[108:109], 0
	v_mov_b64_e32 v[110:111], 0
	v_mov_b64_e32 v[112:113], 0
	v_mov_b64_e32 v[114:115], 0
	v_mov_b64_e32 v[116:117], 0
	v_mov_b64_e32 v[118:119], 0
	v_mov_b64_e32 v[120:121], 0
	v_mov_b64_e32 v[122:123], 0
	v_mov_b64_e32 v[124:125], 0
	v_mov_b64_e32 v[126:127], 0

.LBB0_635:
	s_ashr_i32 s13, s12, 31
	s_lshl_b64 s[14:15], s[12:13], 19
	s_add_u32 s14, s64, s14
	s_addc_u32 s15, s65, s15
	s_and_b64 s[16:17], s[2:3], exec
	s_cselect_b32 s13, s15, s1
	s_cselect_b32 s48, s14, s0
	s_ashr_i32 s11, s10, 31
	s_lshl_b64 s[16:17], s[10:11], 19
	s_add_u32 s16, s36, s16
	s_addc_u32 s17, s37, s17
	s_and_b64 s[34:35], s[2:3], exec
	s_cselect_b32 s11, s17, s31
	s_cselect_b32 s49, s16, s30
	s_add_u32 s0, s0, 0x40080
	s_addc_u32 s1, s1, 0
	s_add_u32 s50, s30, 0x100
	s_addc_u32 s51, s31, 0
	s_mov_b32 s52, -2
	s_waitcnt vmcnt(0)
	v_mov_b64_e32 v[0:1], 0
	v_mov_b64_e32 v[2:3], 0
	v_mov_b64_e32 v[4:5], 0
	v_mov_b64_e32 v[6:7], 0
	v_mov_b64_e32 v[8:9], 0
	v_mov_b64_e32 v[10:11], 0
	v_mov_b64_e32 v[12:13], 0
	v_mov_b64_e32 v[14:15], 0
	v_mov_b64_e32 v[16:17], 0
	v_mov_b64_e32 v[18:19], 0
	v_mov_b64_e32 v[20:21], 0
	v_mov_b64_e32 v[22:23], 0
	v_mov_b64_e32 v[24:25], 0
	v_mov_b64_e32 v[26:27], 0
	v_mov_b64_e32 v[28:29], 0
	v_mov_b64_e32 v[30:31], 0
	v_mov_b64_e32 v[32:33], 0
	v_mov_b64_e32 v[34:35], 0
	v_mov_b64_e32 v[36:37], 0
	v_mov_b64_e32 v[38:39], 0
	v_mov_b64_e32 v[40:41], 0
	v_mov_b64_e32 v[42:43], 0
	v_mov_b64_e32 v[44:45], 0
	v_mov_b64_e32 v[46:47], 0
	v_mov_b64_e32 v[48:49], 0
	v_mov_b64_e32 v[50:51], 0
	v_mov_b64_e32 v[52:53], 0
	v_mov_b64_e32 v[54:55], 0
	v_mov_b64_e32 v[56:57], 0
	v_mov_b64_e32 v[58:59], 0
	v_mov_b64_e32 v[60:61], 0
	v_mov_b64_e32 v[62:63], 0
	v_mov_b64_e32 v[64:65], 0
	v_mov_b64_e32 v[66:67], 0
	v_mov_b64_e32 v[68:69], 0
	v_mov_b64_e32 v[70:71], 0
	v_mov_b64_e32 v[72:73], 0
	v_mov_b64_e32 v[74:75], 0
	v_mov_b64_e32 v[76:77], 0
	v_mov_b64_e32 v[78:79], 0
	v_mov_b64_e32 v[80:81], 0
	v_mov_b64_e32 v[82:83], 0
	v_mov_b64_e32 v[84:85], 0
	v_mov_b64_e32 v[86:87], 0
	v_mov_b64_e32 v[88:89], 0
	v_mov_b64_e32 v[90:91], 0
	v_mov_b64_e32 v[92:93], 0
	v_mov_b64_e32 v[94:95], 0
	v_mov_b64_e32 v[96:97], 0
	v_mov_b64_e32 v[98:99], 0
	v_mov_b64_e32 v[100:101], 0
	v_mov_b64_e32 v[102:103], 0
	v_mov_b64_e32 v[104:105], 0
	v_mov_b64_e32 v[106:107], 0
	v_mov_b64_e32 v[108:109], 0
	v_mov_b64_e32 v[110:111], 0
	v_mov_b64_e32 v[112:113], 0
	v_mov_b64_e32 v[114:115], 0
	v_mov_b64_e32 v[116:117], 0
	v_mov_b64_e32 v[118:119], 0
	v_mov_b64_e32 v[120:121], 0
	v_mov_b64_e32 v[122:123], 0
	v_mov_b64_e32 v[124:125], 0
	v_mov_b64_e32 v[126:127], 0

.LBB0_710:
	s_ashr_i32 s17, s16, 31
	s_lshl_b64 s[26:27], s[16:17], 21
	s_add_u32 s26, s92, s26
	s_addc_u32 s27, s93, s27
	s_and_b64 s[28:29], s[6:7], exec
	s_cselect_b32 s17, s27, s1
	s_cselect_b32 s33, s26, s0
	s_ashr_i32 s15, s14, 31
	s_lshl_b64 s[28:29], s[14:15], 21
	s_add_u32 s28, s56, s28
	s_addc_u32 s29, s57, s29
	s_and_b64 s[38:39], s[6:7], exec
	s_cselect_b32 s15, s29, s37
	s_cselect_b32 s55, s28, s36
	s_add_u32 s0, s0, 0x100080
	s_addc_u32 s1, s1, 0
	s_add_u32 s58, s36, 0x100
	s_addc_u32 s59, s37, 0
	s_mov_b32 s60, -2
	s_waitcnt lgkmcnt(0)
	s_waitcnt vmcnt(0)
	v_mov_b64_e32 v[0:1], 0
	v_mov_b64_e32 v[2:3], 0
	v_mov_b64_e32 v[4:5], 0
	v_mov_b64_e32 v[6:7], 0
	v_mov_b64_e32 v[8:9], 0
	v_mov_b64_e32 v[10:11], 0
	v_mov_b64_e32 v[12:13], 0
	v_mov_b64_e32 v[14:15], 0
	v_mov_b64_e32 v[16:17], 0
	v_mov_b64_e32 v[18:19], 0
	v_mov_b64_e32 v[20:21], 0
	v_mov_b64_e32 v[22:23], 0
	v_mov_b64_e32 v[24:25], 0
	v_mov_b64_e32 v[26:27], 0
	v_mov_b64_e32 v[28:29], 0
	v_mov_b64_e32 v[30:31], 0
	v_mov_b64_e32 v[32:33], 0
	v_mov_b64_e32 v[34:35], 0
	v_mov_b64_e32 v[36:37], 0
	v_mov_b64_e32 v[38:39], 0
	v_mov_b64_e32 v[40:41], 0
	v_mov_b64_e32 v[42:43], 0
	v_mov_b64_e32 v[44:45], 0
	v_mov_b64_e32 v[46:47], 0
	v_mov_b64_e32 v[48:49], 0
	v_mov_b64_e32 v[50:51], 0
	v_mov_b64_e32 v[52:53], 0
	v_mov_b64_e32 v[54:55], 0
	v_mov_b64_e32 v[56:57], 0
	v_mov_b64_e32 v[58:59], 0
	v_mov_b64_e32 v[60:61], 0
	v_mov_b64_e32 v[62:63], 0
	v_mov_b64_e32 v[64:65], 0
	v_mov_b64_e32 v[66:67], 0
	v_mov_b64_e32 v[68:69], 0
	v_mov_b64_e32 v[70:71], 0
	v_mov_b64_e32 v[72:73], 0
	v_mov_b64_e32 v[74:75], 0
	v_mov_b64_e32 v[76:77], 0
	v_mov_b64_e32 v[78:79], 0
	v_mov_b64_e32 v[80:81], 0
	v_mov_b64_e32 v[82:83], 0
	v_mov_b64_e32 v[84:85], 0
	v_mov_b64_e32 v[86:87], 0
	v_mov_b64_e32 v[88:89], 0
	v_mov_b64_e32 v[90:91], 0
	v_mov_b64_e32 v[92:93], 0
	v_mov_b64_e32 v[94:95], 0
	v_mov_b64_e32 v[96:97], 0
	v_mov_b64_e32 v[98:99], 0
	v_mov_b64_e32 v[100:101], 0
	v_mov_b64_e32 v[102:103], 0
	v_mov_b64_e32 v[104:105], 0
	v_mov_b64_e32 v[106:107], 0
	v_mov_b64_e32 v[108:109], 0
	v_mov_b64_e32 v[110:111], 0
	v_mov_b64_e32 v[112:113], 0
	v_mov_b64_e32 v[114:115], 0
	v_mov_b64_e32 v[116:117], 0
	v_mov_b64_e32 v[118:119], 0
	v_mov_b64_e32 v[120:121], 0
	v_mov_b64_e32 v[122:123], 0
	v_mov_b64_e32 v[124:125], 0
	v_mov_b64_e32 v[126:127], 0

.LBB0_798:
	s_ashr_i32 s29, s28, 31
	s_lshl_b64 s[30:31], s[28:29], 19
	s_add_u32 s30, s96, s30
	s_addc_u32 s31, s97, s31
	s_and_b64 s[34:35], s[4:5], exec
	s_cselect_b32 s3, s31, s1
	s_cselect_b32 s7, s30, s0
	s_ashr_i32 s27, s26, 31
	s_lshl_b64 s[34:35], s[26:27], 19
	s_add_u32 s34, s58, s34
	s_addc_u32 s35, s59, s35
	s_and_b64 s[36:37], s[4:5], exec
	s_cselect_b32 s27, s35, s9
	s_cselect_b32 s29, s34, s8
	s_add_u32 s0, s0, 0x40080
	s_addc_u32 s1, s1, 0
	s_add_u32 s33, s8, 0x100
	s_addc_u32 s38, s9, 0
	s_mov_b32 s39, -2
	s_waitcnt vmcnt(0)
	v_mov_b64_e32 v[0:1], 0
	v_mov_b64_e32 v[2:3], 0
	v_mov_b64_e32 v[4:5], 0
	v_mov_b64_e32 v[6:7], 0
	v_mov_b64_e32 v[8:9], 0
	v_mov_b64_e32 v[10:11], 0
	v_mov_b64_e32 v[12:13], 0
	v_mov_b64_e32 v[14:15], 0
	v_mov_b64_e32 v[16:17], 0
	v_mov_b64_e32 v[18:19], 0
	v_mov_b64_e32 v[20:21], 0
	v_mov_b64_e32 v[22:23], 0
	v_mov_b64_e32 v[24:25], 0
	v_mov_b64_e32 v[26:27], 0
	v_mov_b64_e32 v[28:29], 0
	v_mov_b64_e32 v[30:31], 0
	v_mov_b64_e32 v[32:33], 0
	v_mov_b64_e32 v[34:35], 0
	v_mov_b64_e32 v[36:37], 0
	v_mov_b64_e32 v[38:39], 0
	v_mov_b64_e32 v[40:41], 0
	v_mov_b64_e32 v[42:43], 0
	v_mov_b64_e32 v[44:45], 0
	v_mov_b64_e32 v[46:47], 0
	v_mov_b64_e32 v[48:49], 0
	v_mov_b64_e32 v[50:51], 0
	v_mov_b64_e32 v[52:53], 0
	v_mov_b64_e32 v[54:55], 0
	v_mov_b64_e32 v[56:57], 0
	v_mov_b64_e32 v[58:59], 0
	v_mov_b64_e32 v[60:61], 0
	v_mov_b64_e32 v[62:63], 0
	v_mov_b64_e32 v[64:65], 0
	v_mov_b64_e32 v[66:67], 0
	v_mov_b64_e32 v[68:69], 0
	v_mov_b64_e32 v[70:71], 0
	v_mov_b64_e32 v[72:73], 0
	v_mov_b64_e32 v[74:75], 0
	v_mov_b64_e32 v[76:77], 0
	v_mov_b64_e32 v[78:79], 0
	v_mov_b64_e32 v[80:81], 0
	v_mov_b64_e32 v[82:83], 0
	v_mov_b64_e32 v[84:85], 0
	v_mov_b64_e32 v[86:87], 0
	v_mov_b64_e32 v[88:89], 0
	v_mov_b64_e32 v[90:91], 0
	v_mov_b64_e32 v[92:93], 0
	v_mov_b64_e32 v[94:95], 0
	v_mov_b64_e32 v[96:97], 0
	v_mov_b64_e32 v[98:99], 0
	v_mov_b64_e32 v[100:101], 0
	v_mov_b64_e32 v[102:103], 0
	v_mov_b64_e32 v[104:105], 0
	v_mov_b64_e32 v[106:107], 0
	v_mov_b64_e32 v[108:109], 0
	v_mov_b64_e32 v[110:111], 0
	v_mov_b64_e32 v[112:113], 0
	v_mov_b64_e32 v[114:115], 0
	v_mov_b64_e32 v[116:117], 0
	v_mov_b64_e32 v[118:119], 0
	v_mov_b64_e32 v[120:121], 0
	v_mov_b64_e32 v[122:123], 0
	v_mov_b64_e32 v[124:125], 0
	v_mov_b64_e32 v[126:127], 0

.LBB0_1284:
	s_ashr_i32 s84, s68, 6
	s_lshl_b32 s16, s84, 3
	v_bfe_u32 v180, v18, 4, 2
	v_and_b32_e32 v4, 15, v18
	v_or_b32_e32 v12, s16, v180
	v_lshlrev_b32_e32 v6, 5, v180
	v_lshlrev_b32_e32 v3, 3, v4
	v_xor_b32_e32 v14, v6, v3
	v_min_i32_e32 v6, 15, v12
	v_or_b32_e32 v13, 4, v12
	v_bitop3_b32 v0, v12, v18, 4 bitop3:0x36
	v_ashrrev_i32_e32 v7, 31, v6
	v_bitop3_b32 v5, v12, v4, 11 bitop3:0x6c
	v_lshlrev_b32_e32 v0, 3, v0
	v_min_i32_e32 v8, 15, v13
	v_lshlrev_b64 v[6:7], 11, v[6:7]
	v_and_b32_e32 v15, 0x78, v0
	v_lshl_add_u64 v[10:11], s[10:11], 0, v[6:7]
	v_lshlrev_b32_e32 v0, 4, v5
	v_ashrrev_i32_e32 v9, 31, v8
	s_lshl_b32 s87, s84, 11
	v_lshl_add_u64 v[10:11], v[10:11], 0, v[0:1]
	v_lshlrev_b64 v[8:9], 11, v[8:9]
	s_add_i32 s87, s87, 0
	s_mov_b32 s21, m0
	s_mov_b32 m0, s87
	s_nop 0
	global_load_lds_dwordx4 v[10:11], off
	s_mov_b32 m0, s21
	v_lshl_add_u64 v[10:11], s[10:11], 0, v[8:9]
	v_lshlrev_b32_e32 v152, 1, v15
	v_mov_b32_e32 v153, v1
	v_lshl_add_u64 v[6:7], s[8:9], 0, v[6:7]
	v_lshlrev_b32_e32 v154, 1, v14
	v_mov_b32_e32 v155, v1
	v_lshl_add_u64 v[10:11], v[10:11], 0, v[152:153]
	s_add_i32 s10, s87, 0x400
	s_mov_b32 s11, m0
	s_mov_b32 m0, s10
	s_nop 0
	global_load_lds_dwordx4 v[10:11], off
	s_mov_b32 m0, s11
	v_lshl_add_u64 v[6:7], v[6:7], 0, v[154:155]
	s_add_i32 s85, s87, 0xc000
	s_mov_b32 s10, m0
	s_mov_b32 m0, s85
	s_nop 0
	global_load_lds_dwordx4 v[6:7], off
	s_mov_b32 m0, s10
	v_lshl_add_u64 v[6:7], s[8:9], 0, v[8:9]
	v_lshl_add_u64 v[6:7], v[6:7], 0, v[154:155]
	s_add_i32 s8, s87, 0xc400
	s_mov_b32 s9, m0
	s_mov_b32 m0, s8
	s_nop 0
	global_load_lds_dwordx4 v[6:7], off
	s_mov_b32 m0, s9
	v_min_i32_e32 v6, 63, v12
	v_ashrrev_i32_e32 v7, 31, v6
	v_min_i32_e32 v8, 63, v13
	v_lshlrev_b64 v[20:21], 11, v[6:7]
	v_lshl_add_u64 v[6:7], s[0:1], 0, v[20:21]
	v_ashrrev_i32_e32 v9, 31, v8
	v_lshl_add_u64 v[6:7], v[6:7], 0, v[0:1]
	v_lshlrev_b64 v[22:23], 11, v[8:9]
	s_add_i32 s8, s87, 0x4000
	s_mov_b32 s9, m0
	s_mov_b32 m0, s8
	s_nop 0
	global_load_lds_dwordx4 v[6:7], off
	s_mov_b32 m0, s9
	v_lshl_add_u64 v[6:7], s[0:1], 0, v[22:23]
	v_lshl_add_u64 v[6:7], v[6:7], 0, v[152:153]
	s_add_i32 s8, s87, 0x4400
	s_mov_b32 s9, m0
	s_mov_b32 m0, s8
	s_nop 0
	global_load_lds_dwordx4 v[6:7], off
	s_mov_b32 m0, s9
	v_lshl_add_u64 v[6:7], s[6:7], 0, v[20:21]
	v_lshl_add_u64 v[6:7], v[6:7], 0, v[154:155]
	s_add_i32 s8, s87, 0x10000
	s_mov_b32 s9, m0
	s_mov_b32 m0, s8
	s_nop 0
	global_load_lds_dwordx4 v[6:7], off
	s_mov_b32 m0, s9
	v_lshl_add_u64 v[6:7], s[6:7], 0, v[22:23]
	v_lshl_add_u64 v[6:7], v[6:7], 0, v[154:155]
	s_add_i32 s8, s87, 0x10400
	s_mov_b32 s9, m0
	s_mov_b32 m0, s8
	s_nop 0
	global_load_lds_dwordx4 v[6:7], off
	s_mov_b32 m0, s9
	v_cmp_gt_i32_e32 vcc, s24, v18
	s_and_saveexec_b64 s[8:9], vcc
	s_cbranch_execz .Latt_pro_nolut
	v_ashrrev_i32_e32 v19, 31, v18
	v_lshl_add_u64 v[6:7], v[18:19], 2, s[14:15]
	global_load_dword v0, v[6:7], off
.Latt_pro_nolut:
	s_or_b64 exec, exec, s[8:9]
	s_cmp_eq_u32 s19, 4
	s_cbranch_scc0 .Latt_pro_generic
	v_lshlrev_b32_e32 v7, 1, v3
	v_ashrrev_i32_e32 v12, 4, v18
	v_lshl_add_u32 v8, v12, 11, v7
	v_add_u32_e32 v9, 0x10000, v8
	v_add_u32_e32 v10, 0x20000, v8
	v_add_u32_e32 v11, 0x30000, v8
	global_load_dwordx4 v[188:191], v8, s[4:5]
	global_load_dwordx4 v[192:195], v9, s[4:5]
	global_load_dwordx4 v[196:199], v10, s[4:5]
	global_load_dwordx4 v[200:203], v11, s[4:5]
	v_mad_u32_u24 v13, v12, s77, v7
	v_add_u32_e32 v13, 0x18400, v13
	v_lshl_add_u32 v6, v18, 2, 0
	v_add_u32_e32 v6, 0x20c00, v6
	s_waitcnt vmcnt(0)
	v_sub_f32_e32 v0, v0, v2
	v_cmp_gt_i32_e32 vcc, s24, v18
	s_and_saveexec_b64 s[8:9], vcc
	ds_write_b32 v6, v0
	s_or_b64 exec, exec, s[8:9]
	ds_write_b128 v13, v[188:191]
	ds_write_b128 v13, v[192:195] offset:8704
	ds_write_b128 v13, v[196:199] offset:17408
	ds_write_b128 v13, v[200:203] offset:26112
	s_mov_b64 s[8:9], exec
	s_branch .LBB0_1289
.Latt_pro_generic:
	v_lshl_add_u32 v6, v18, 2, 0
	v_add_u32_e32 v6, 0x20c00, v6
	s_waitcnt vmcnt(0)
	v_sub_f32_e32 v0, v0, v2
	v_cmp_gt_i32_e32 vcc, s24, v18
	s_and_saveexec_b64 s[8:9], vcc
	ds_write_b32 v6, v0
	s_or_b64 exec, exec, s[8:9]
	s_lshl_b32 s10, s19, 9
	v_cmp_gt_i32_e32 vcc, s10, v18
	s_and_saveexec_b64 s[8:9], vcc
	s_cbranch_execz .LBB0_1289
	v_lshlrev_b32_e32 v0, 1, v3
	s_waitcnt vmcnt(0)
	v_lshl_add_u64 v[2:3], s[4:5], 0, v[0:1]
	v_readlane_b32 s4, v238, 40
	v_mov_b32_e32 v6, v18
	s_nop 0
	v_lshl_add_u32 v0, v4, 4, s4
	s_mov_b64 s[4:5], 0

.LBB0_1294:
	v_lshlrev_b32_e32 v8, 2, v17
	v_bfe_u32 v3, v18, 2, 2
	v_lshlrev_b32_e32 v5, 1, v180
	v_bfe_u32 v6, v18, 1, 1
	v_or_b32_e32 v4, v8, v3
	v_and_or_b32 v5, v5, 2, v6
	v_lshlrev_b32_e32 v6, 3, v18
	v_lshlrev_b32_e32 v3, 6, v3
	v_lshlrev_b32_e32 v4, 8, v4
	v_lshlrev_b32_e32 v5, 4, v5
	v_and_or_b32 v3, v6, 8, v3
	v_or3_b32 v7, v3, v4, v5
	s_movk_i32 s11, 0x80
	v_add_u32_e32 v2, s17, v162
	v_bitop3_b32 v9, v7, 64, v158 bitop3:0x36
	v_bitop3_b32 v10, v7, s11, v158 bitop3:0x36
	s_and_b64 vcc, exec, s[4:5]
	v_bitop3_b32 v11, v7, s24, v158 bitop3:0x36
	s_cbranch_vccnz .LBB0_1299
	s_cmpk_gt_i32 s17, 0xae
	s_cbranch_scc1 .LBB0_1297
	v_or_b32_e32 v3, 0x80, v8
	v_sub_u32_e32 v3, v3, v2
	v_add_u32_e32 v3, -16, v3
	v_max_i32_e32 v4, 0, v3
	s_add_i32 s4, 0, 0x20c00
	v_lshl_add_u32 v6, v4, 2, s4
	v_max_i32_e32 v4, -1, v3
	v_lshl_add_u32 v17, v4, 2, s4
	v_max_i32_e32 v4, -2, v3
	v_max_i32_e32 v5, -3, v3
	v_max_i32_e32 v12, -8, v3
	v_max_i32_e32 v13, -9, v3
	v_max_i32_e32 v14, -10, v3
	v_lshl_add_u32 v4, v4, 2, s4
	v_lshl_add_u32 v5, v5, 2, s4
	v_lshl_add_u32 v12, v12, 2, s4
	v_lshl_add_u32 v13, v13, 2, s4
	v_lshl_add_u32 v14, v14, 2, s4
	v_max_i32_e32 v3, -11, v3
	v_lshl_add_u32 v3, v3, 2, s4
	ds_read_b32 v4, v4 offset:8
	ds_read_b32 v5, v5 offset:12
	ds_read_b32 v12, v12 offset:32
	ds_read_b32 v14, v14 offset:40
	ds_read_b32 v15, v3 offset:44
	ds_read_b32 v13, v13 offset:36
	ds_read_b32 v18, v6
	ds_read_b32 v19, v17 offset:4
	s_waitcnt lgkmcnt(6)
	v_pk_add_f32 v[98:99], v[98:99], v[4:5]
	s_waitcnt lgkmcnt(3)
	v_pk_add_f32 v[102:103], v[102:103], v[14:15]
	s_waitcnt lgkmcnt(2)
	v_pk_add_f32 v[100:101], v[100:101], v[12:13]
	s_waitcnt lgkmcnt(0)
	v_pk_add_f32 v[96:97], v[96:97], v[18:19]

.LBB0_1304:
	s_cmp_eq_u32 s89, 0
	s_cbranch_scc0 .Latt_slow
	s_cmp_eq_u32 s91, 0
	s_cbranch_scc0 .Latt_slow
	s_sub_i32 s4, s70, s95
	s_sub_i32 s4, s4, 1
	s_lshr_b32 s5, s90, 6
	s_min_i32 s4, s4, s5
	s_lshl_b32 s5, s94, 5
	s_sub_i32 s5, s93, s5
	s_ashr_i32 s5, s5, 6
	s_sub_i32 s5, s5, 1
	s_min_i32 s4, s4, s5
	s_ashr_i32 s5, s33, 6
	s_min_i32 s4, s4, s5
	s_cmp_gt_i32 s4, 0
	s_cbranch_scc0 .Latt_slow
	s_mov_b32 s100, s4
	s_mov_b32 s101, s4
	s_branch .Latt_flA_top

.LBB0_1306:
	s_add_i32 s6, s95, 2
	s_cmp_le_u32 s6, s70
	s_cselect_b64 s[74:75], -1, 0
	s_cmp_gt_u32 s6, s70
	s_cbranch_scc1 .LBB0_1310
	v_cmp_lt_i64_e64 s[6:7], s[90:91], 64
	s_and_b64 s[6:7], s[6:7], exec
	s_cselect_b32 s6, s90, 64
	s_cselect_b32 s7, s91, 0
	s_add_u32 s6, s6, -1
	s_addc_u32 s7, s7, -1
	v_mov_b32_e32 v153, s7
	v_cmp_lt_i64_e32 vcc, s[6:7], v[2:3]
	v_mov_b32_e32 v155, s6
	s_nop 0
	v_cndmask_b32_e32 v181, v3, v153, vcc
	v_cndmask_b32_e32 v180, v2, v155, vcc
	v_cmp_lt_i64_e32 vcc, s[6:7], v[4:5]
	v_lshlrev_b64 v[180:181], 11, v[180:181]
	v_lshl_add_u64 v[188:189], s[0:1], 0, v[180:181]
	v_cndmask_b32_e32 v191, v5, v153, vcc
	v_cndmask_b32_e32 v190, v4, v155, vcc
	v_lshlrev_b64 v[190:191], 11, v[190:191]
	v_lshl_add_u64 v[192:193], s[0:1], 0, v[190:191]
	v_lshl_add_u64 v[180:181], s[66:67], 0, v[180:181]
	v_lshl_add_u64 v[190:191], s[66:67], 0, v[190:191]
	s_setprio 1
	v_lshl_add_u64 v[188:189], v[188:189], 0, s[72:73]
	s_lshl_b32 s6, s88, 14
	v_lshl_add_u64 v[188:189], v[188:189], 0, v[0:1]
	s_add_i32 s7, s87, s6
	s_mov_b32 s8, m0
	s_mov_b32 m0, s7
	s_nop 0
	global_load_lds_dwordx4 v[188:189], off
	s_mov_b32 m0, s8
	v_lshl_add_u64 v[188:189], v[192:193], 0, s[72:73]
	v_mov_b32_e32 v153, v1
	v_lshl_add_u64 v[180:181], v[180:181], 0, s[72:73]
	v_mov_b32_e32 v155, v1
	v_lshl_add_u64 v[188:189], v[188:189], 0, v[152:153]
	s_addk_i32 s7, 0x400
	s_mov_b32 s8, m0
	s_mov_b32 m0, s7
	s_nop 0
	global_load_lds_dwordx4 v[188:189], off
	s_mov_b32 m0, s8
	v_lshl_add_u64 v[180:181], v[180:181], 0, v[154:155]
	s_add_i32 s6, s95, 2
	s_and_b32 s6, s6, 3
	s_lshl_b32 s6, s6, 14
	s_add_i32 s6, s85, s6
	s_mov_b32 s7, m0
	s_mov_b32 m0, s6
	s_nop 0
	global_load_lds_dwordx4 v[180:181], off
	s_mov_b32 m0, s7
	v_lshl_add_u64 v[180:181], v[190:191], 0, s[72:73]
	v_lshl_add_u64 v[180:181], v[180:181], 0, v[154:155]
	s_addk_i32 s6, 0x400
	s_mov_b32 s7, m0
	s_mov_b32 m0, s6
	s_nop 0
	global_load_lds_dwordx4 v[180:181], off
	s_mov_b32 m0, s7
	s_setprio 0
	s_and_b64 vcc, exec, s[4:5]
	s_cbranch_vccz .LBB0_1311

.LBB0_1311:
	s_cmpk_gt_i32 s93, 0x7f
	s_cbranch_scc1 .LBB0_1313
	v_max_i32_e32 v202, -3, v179
	v_add_u32_e32 v202, 3, v202
	s_add_i32 s4, 0, 0x20c00
	v_min_u32_e32 v202, 0xbf, v202
	v_lshl_add_u32 v213, v202, 2, s4
	v_max_i32_e32 v202, -8, v179
	v_add_u32_e32 v202, 8, v202
	v_subrev_u32_e32 v153, 32, v179
	v_min_u32_e32 v202, 0xbf, v202
	v_max_i32_e32 v180, -1, v153
	v_lshl_add_u32 v214, v202, 2, s4
	v_max_i32_e32 v202, -9, v179
	v_lshl_add_u32 v181, v180, 2, s4
	v_max_i32_e32 v180, -2, v153
	v_add_u32_e32 v202, 9, v202
	v_lshl_add_u32 v187, v180, 2, s4
	v_max_i32_e32 v180, -3, v153
	v_min_u32_e32 v202, 0xbf, v202
	v_lshl_add_u32 v189, v180, 2, s4
	v_max_i32_e32 v180, -8, v153
	v_lshl_add_u32 v215, v202, 2, s4
	v_max_i32_e32 v202, -10, v179
	v_lshl_add_u32 v190, v180, 2, s4
	v_max_i32_e32 v180, -9, v153
	v_max_i32_e32 v194, 0xffffffee, v153
	v_add_u32_e32 v202, 10, v202
	v_lshl_add_u32 v191, v180, 2, s4
	v_max_i32_e32 v180, -10, v153
	v_lshl_add_u32 v196, v194, 2, s4
	v_max_i32_e32 v194, 0xffffffed, v153
	v_min_u32_e32 v202, 0xbf, v202
	v_max_i32_e32 v155, 0, v153
	v_lshl_add_u32 v192, v180, 2, s4
	v_max_i32_e32 v180, -11, v153
	v_lshl_add_u32 v197, v194, 2, s4
	v_max_i32_e32 v194, 0xffffffe8, v153
	v_lshl_add_u32 v216, v202, 2, s4
	v_max_i32_e32 v202, -11, v179
	v_lshl_add_u32 v155, v155, 2, s4
	v_lshl_add_u32 v193, v180, 2, s4
	v_lshl_add_u32 v198, v194, 2, s4
	v_max_i32_e32 v194, 0xffffffe7, v153
	v_add_u32_e32 v202, 11, v202
	ds_read_b32 v180, v155
	ds_read_b32 v181, v181 offset:4
	ds_read_b32 v188, v187 offset:8
	ds_read_b32 v189, v189 offset:12
	ds_read_b32 v190, v190 offset:32
	ds_read_b32 v191, v191 offset:36
	ds_read_b32 v192, v192 offset:40
	ds_read_b32 v193, v193 offset:44
	v_max_i32_e32 v155, -16, v153
	v_max_i32_e32 v187, 0xffffffef, v153
	v_lshl_add_u32 v199, v194, 2, s4
	v_max_i32_e32 v194, 0xffffffe6, v153
	v_min_u32_e32 v202, 0xbf, v202
	v_lshl_add_u32 v155, v155, 2, s4
	v_lshl_add_u32 v187, v187, 2, s4
	v_lshl_add_u32 v200, v194, 2, s4
	v_max_i32_e32 v153, 0xffffffe5, v153
	v_lshl_add_u32 v217, v202, 2, s4
	v_max_i32_e32 v202, -16, v179
	v_max_i32_e32 v203, 0xffffffef, v179
	v_max_i32_e32 v204, 0xffffffee, v179
	v_max_i32_e32 v205, 0xffffffed, v179
	v_max_i32_e32 v206, 0xffffffe8, v179
	v_max_i32_e32 v207, 0xffffffe7, v179
	v_max_i32_e32 v208, 0xffffffe6, v179
	v_max_i32_e32 v209, 0xffffffe5, v179
	v_lshl_add_u32 v153, v153, 2, s4
	ds_read_b32 v194, v155 offset:64
	ds_read_b32 v195, v187 offset:68
	ds_read_b32 v196, v196 offset:72
	ds_read_b32 v197, v197 offset:76
	ds_read_b32 v198, v198 offset:96
	ds_read_b32 v199, v199 offset:100
	ds_read_b32 v200, v200 offset:104
	ds_read_b32 v201, v153 offset:108
	v_max_i32_e32 v155, -1, v179
	v_max_i32_e32 v187, -2, v179
	v_add_u32_e32 v202, 16, v202
	v_add_u32_e32 v203, 17, v203
	v_add_u32_e32 v204, 18, v204
	v_add_u32_e32 v205, 19, v205
	v_add_u32_e32 v206, 24, v206
	v_add_u32_e32 v207, 25, v207
	v_add_u32_e32 v208, 26, v208
	v_add_u32_e32 v209, 27, v209
	v_add_u32_e32 v155, 1, v155
	v_add_u32_e32 v187, 2, v187
	v_min_u32_e32 v202, 0xbf, v202
	v_min_u32_e32 v203, 0xbf, v203
	v_min_u32_e32 v204, 0xbf, v204
	v_min_u32_e32 v205, 0xbf, v205
	v_min_u32_e32 v206, 0xbf, v206
	v_min_u32_e32 v207, 0xbf, v207
	v_min_u32_e32 v208, 0xbf, v208
	v_min_u32_e32 v209, 0xbf, v209
	v_med3_i32 v153, v179, 0, v159
	v_min_u32_e32 v155, 0xbf, v155
	v_min_u32_e32 v187, 0xbf, v187
	v_lshl_add_u32 v202, v202, 2, s4
	v_lshl_add_u32 v203, v203, 2, s4
	v_lshl_add_u32 v204, v204, 2, s4
	v_lshl_add_u32 v205, v205, 2, s4
	v_lshl_add_u32 v206, v206, 2, s4
	v_lshl_add_u32 v207, v207, 2, s4
	v_lshl_add_u32 v208, v208, 2, s4
	v_lshl_add_u32 v209, v209, 2, s4
	v_lshl_add_u32 v153, v153, 2, s4
	v_lshl_add_u32 v155, v155, 2, s4
	v_lshl_add_u32 v187, v187, 2, s4
	ds_read_b32 v202, v202
	ds_read_b32 v203, v203
	ds_read_b32 v204, v204
	ds_read_b32 v205, v205
	ds_read_b32 v206, v206
	ds_read_b32 v207, v207
	ds_read_b32 v208, v208
	ds_read_b32 v209, v209
	ds_read_b32 v210, v153
	ds_read_b32 v211, v155
	ds_read_b32 v212, v187
	ds_read_b32 v213, v213
	ds_read_b32 v214, v214
	ds_read_b32 v215, v215
	ds_read_b32 v216, v216
	ds_read_b32 v217, v217
	s_waitcnt lgkmcnt(8)
	v_pk_add_f32 v[126:127], v[126:127], v[208:209]
	v_pk_add_f32 v[124:125], v[124:125], v[206:207]
	v_pk_add_f32 v[122:123], v[122:123], v[204:205]
	v_pk_add_f32 v[120:121], v[120:121], v[202:203]
	s_waitcnt lgkmcnt(0)
	v_pk_add_f32 v[118:119], v[118:119], v[216:217]
	v_pk_add_f32 v[116:117], v[116:117], v[214:215]
	v_pk_add_f32 v[114:115], v[114:115], v[212:213]
	v_pk_add_f32 v[112:113], v[112:113], v[210:211]
	v_pk_add_f32 v[110:111], v[110:111], v[200:201]
	v_pk_add_f32 v[108:109], v[108:109], v[198:199]
	v_pk_add_f32 v[106:107], v[106:107], v[196:197]
	v_pk_add_f32 v[104:105], v[104:105], v[194:195]
	v_pk_add_f32 v[102:103], v[102:103], v[192:193]
	v_pk_add_f32 v[100:101], v[100:101], v[190:191]
	v_pk_add_f32 v[98:99], v[98:99], v[188:189]
	v_pk_add_f32 v[96:97], v[96:97], v[180:181]

.LBB0_1315:
	s_and_b32 s4, s95, 3
	s_lshl_b32 s4, s4, 14
	v_add_u32_e32 v213, s4, v7
	v_exp_f32_e32 v153, v96
	v_exp_f32_e32 v155, v97
	v_exp_f32_e32 v180, v98
	v_exp_f32_e32 v181, v99
	v_exp_f32_e32 v187, v100
	v_exp_f32_e32 v212, v101
	ds_read_b64_tr_b16 v[188:189], v213 offset:49152
	ds_read_b64_tr_b16 v[190:191], v213 offset:51200
	v_exp_f32_e32 v214, v102
	v_exp_f32_e32 v215, v103
	v_cvt_pk_bf16_f32 v192, v153, v155
	v_cvt_pk_bf16_f32 v193, v180, v181
	v_cvt_pk_bf16_f32 v194, v187, v212
	v_cvt_pk_bf16_f32 v195, v214, v215
	v_add_u32_e32 v216, s4, v9
	ds_read_b64_tr_b16 v[196:197], v213 offset:53248
	ds_read_b64_tr_b16 v[198:199], v213 offset:55296
	s_waitcnt lgkmcnt(2)
	v_mfma_f32_32x32x16_bf16 v[80:95], v[188:191], v[192:195], v[80:95]
	ds_read_b64_tr_b16 v[188:189], v216
	ds_read_b64_tr_b16 v[190:191], v216 offset:2048
	ds_read_b64_tr_b16 v[200:201], v216 offset:4096
	ds_read_b64_tr_b16 v[202:203], v216 offset:6144
	v_add_u32_e32 v217, s4, v10
	v_add_u32_e32 v218, s4, v11
	v_exp_f32_e32 v219, v104
	v_exp_f32_e32 v220, v105
	v_exp_f32_e32 v221, v106
	v_exp_f32_e32 v222, v107
	s_waitcnt lgkmcnt(2)
	v_mfma_f32_32x32x16_bf16 v[64:79], v[188:191], v[192:195], v[64:79]
	ds_read_b64_tr_b16 v[188:189], v217
	ds_read_b64_tr_b16 v[190:191], v217 offset:2048
	ds_read_b64_tr_b16 v[204:205], v217 offset:4096
	ds_read_b64_tr_b16 v[206:207], v217 offset:6144
	v_exp_f32_e32 v223, v108
	v_exp_f32_e32 v224, v109
	v_exp_f32_e32 v225, v110
	v_exp_f32_e32 v226, v111
	v_add_f32_e32 v153, 0, v153
	v_add_f32_e32 v153, v155, v153
	s_waitcnt lgkmcnt(2)
	v_mfma_f32_32x32x16_bf16 v[48:63], v[188:191], v[192:195], v[48:63]
	ds_read_b64_tr_b16 v[188:189], v218
	ds_read_b64_tr_b16 v[190:191], v218 offset:2048
	ds_read_b64_tr_b16 v[208:209], v218 offset:4096
	ds_read_b64_tr_b16 v[210:211], v218 offset:6144
	v_add_f32_e32 v153, v180, v153
	v_add_f32_e32 v153, v181, v153
	v_exp_f32_e32 v227, v112
	v_exp_f32_e32 v228, v113
	v_exp_f32_e32 v229, v114
	v_exp_f32_e32 v230, v115
	s_waitcnt lgkmcnt(2)
	v_mfma_f32_32x32x16_bf16 v[32:47], v[188:191], v[192:195], v[32:47]
	v_cvt_pk_bf16_f32 v188, v219, v220
	v_cvt_pk_bf16_f32 v189, v221, v222
	v_cvt_pk_bf16_f32 v190, v223, v224
	v_cvt_pk_bf16_f32 v191, v225, v226
	v_exp_f32_e32 v231, v116
	v_exp_f32_e32 v232, v117
	v_exp_f32_e32 v233, v118
	v_mfma_f32_32x32x16_bf16 v[80:95], v[196:199], v[188:191], v[80:95]
	ds_read_b64_tr_b16 v[192:193], v213 offset:57344
	ds_read_b64_tr_b16 v[194:195], v213 offset:59392
	v_exp_f32_e32 v234, v119
	v_add_f32_e32 v153, v187, v153
	v_add_f32_e32 v153, v212, v153
	v_add_f32_e32 v153, v214, v153
	v_add_f32_e32 v153, v215, v153
	v_add_f32_e32 v153, v219, v153
	v_mfma_f32_32x32x16_bf16 v[64:79], v[200:203], v[188:191], v[64:79]
	ds_read_b64_tr_b16 v[196:197], v213 offset:61440
	ds_read_b64_tr_b16 v[198:199], v213 offset:63488
	v_add_f32_e32 v153, v220, v153
	v_add_f32_e32 v153, v221, v153
	v_add_f32_e32 v153, v222, v153
	v_add_f32_e32 v153, v223, v153
	v_add_f32_e32 v153, v224, v153
	v_add_f32_e32 v153, v225, v153
	v_mfma_f32_32x32x16_bf16 v[48:63], v[204:207], v[188:191], v[48:63]
	v_add_f32_e32 v153, v226, v153
	v_add_f32_e32 v153, v227, v153
	v_add_f32_e32 v153, v228, v153
	v_add_f32_e32 v153, v229, v153
	v_add_f32_e32 v153, v230, v153
	v_exp_f32_e32 v155, v120
	v_exp_f32_e32 v180, v121
	s_waitcnt lgkmcnt(4)
	v_mfma_f32_32x32x16_bf16 v[32:47], v[208:211], v[188:191], v[32:47]
	v_cvt_pk_bf16_f32 v188, v227, v228
	v_cvt_pk_bf16_f32 v189, v229, v230
	v_cvt_pk_bf16_f32 v190, v231, v232
	v_cvt_pk_bf16_f32 v191, v233, v234
	v_exp_f32_e32 v181, v122
	v_exp_f32_e32 v187, v123
	v_add_f32_e32 v153, v231, v153
	s_waitcnt lgkmcnt(2)
	v_mfma_f32_32x32x16_bf16 v[80:95], v[192:195], v[188:191], v[80:95]
	ds_read_b64_tr_b16 v[192:193], v216 offset:8192
	ds_read_b64_tr_b16 v[194:195], v216 offset:10240
	ds_read_b64_tr_b16 v[200:201], v217 offset:8192
	ds_read_b64_tr_b16 v[202:203], v217 offset:10240
	ds_read_b64_tr_b16 v[204:205], v216 offset:12288
	ds_read_b64_tr_b16 v[206:207], v216 offset:14336
	v_add_f32_e32 v153, v232, v153
	v_add_f32_e32 v153, v233, v153
	v_add_f32_e32 v153, v234, v153
	v_add_f32_e32 v153, v155, v153
	v_add_f32_e32 v153, v180, v153
	s_waitcnt lgkmcnt(4)
	v_mfma_f32_32x32x16_bf16 v[64:79], v[192:195], v[188:191], v[64:79]
	ds_read_b64_tr_b16 v[192:193], v218 offset:8192
	ds_read_b64_tr_b16 v[194:195], v218 offset:10240
	ds_read_b64_tr_b16 v[208:209], v217 offset:12288
	ds_read_b64_tr_b16 v[210:211], v217 offset:14336
	v_add_f32_e32 v153, v181, v153
	v_add_f32_e32 v153, v187, v153
	s_waitcnt lgkmcnt(6)
	v_mfma_f32_32x32x16_bf16 v[48:63], v[200:203], v[188:191], v[48:63]
	ds_read_b64_tr_b16 v[200:201], v218 offset:12288
	ds_read_b64_tr_b16 v[202:203], v218 offset:14336
	s_waitcnt lgkmcnt(4)
	v_mfma_f32_32x32x16_bf16 v[32:47], v[192:195], v[188:191], v[32:47]
	v_exp_f32_e32 v192, v124
	v_exp_f32_e32 v193, v125
	v_exp_f32_e32 v194, v126
	v_exp_f32_e32 v195, v127
	v_cvt_pk_bf16_f32 v188, v155, v180
	v_cvt_pk_bf16_f32 v189, v181, v187
	v_cvt_pk_bf16_f32 v190, v192, v193
	v_cvt_pk_bf16_f32 v191, v194, v195
	v_add_f32_e32 v153, v192, v153
	v_add_f32_e32 v153, v193, v153
	v_mfma_f32_32x32x16_bf16 v[80:95], v[196:199], v[188:191], v[80:95]
	v_add_f32_e32 v153, v194, v153
	v_add_f32_e32 v153, v195, v153
	v_add_f32_e32 v6, v6, v153
	v_mfma_f32_32x32x16_bf16 v[64:79], v[204:207], v[188:191], v[64:79]
	s_waitcnt lgkmcnt(2)
	v_mfma_f32_32x32x16_bf16 v[48:63], v[208:211], v[188:191], v[48:63]
	s_waitcnt lgkmcnt(0)
	v_mfma_f32_32x32x16_bf16 v[32:47], v[200:203], v[188:191], v[32:47]
	s_andn2_b64 vcc, exec, s[74:75]
	s_mov_b64 s[4:5], -1
	s_cbranch_vccz .LBB0_1309

.Latt_flA_top:
	s_lshl_b32 s6, s8, 14
	v_add_u32_e32 v228, s6, v163
	v_add_u32_e32 v229, s6, v164
	v_add_u32_e32 v230, s6, v165
	v_add_u32_e32 v231, s6, v166
	ds_read_b128 v[96:99], v228
	ds_read_b128 v[200:203], v229
	ds_read_b128 v[204:207], v230
	ds_read_b128 v[208:211], v231
	ds_read_b128 v[112:115], v228 offset:8192
	ds_read_b128 v[216:219], v229 offset:8192
	ds_read_b128 v[220:223], v230 offset:8192
	ds_read_b128 v[224:227], v231 offset:8192
	s_add_u32 s98, s0, s72
	s_addc_u32 s99, s1, s73
	s_lshl_b32 s4, s88, 14
	s_add_i32 s5, s87, s4
	s_mov_b32 m0, s5
	s_add_i32 s4, s95, 2
	s_and_b32 s4, s4, 3
	s_lshl_b32 s4, s4, 14
	s_add_i32 s4, s85, s4
	s_waitcnt lgkmcnt(7)
	v_mfma_f32_32x32x16_bf16 v[96:111], v[96:99], v[132:135], 0
	s_waitcnt lgkmcnt(6)
	v_mfma_f32_32x32x16_bf16 v[96:111], v[200:203], v[136:139], v[96:111]
	s_waitcnt lgkmcnt(5)
	v_mfma_f32_32x32x16_bf16 v[96:111], v[204:207], v[140:143], v[96:111]
	s_waitcnt lgkmcnt(4)
	v_mfma_f32_32x32x16_bf16 v[96:111], v[208:211], v[144:147], v[96:111]
	s_waitcnt lgkmcnt(3)
	v_mfma_f32_32x32x16_bf16 v[112:127], v[112:115], v[132:135], 0
	global_load_lds_dwordx4 v239, s[98:99]
	s_addk_i32 s5, 0x400
	s_mov_b32 m0, s5
	s_waitcnt lgkmcnt(2)
	v_mfma_f32_32x32x16_bf16 v[112:127], v[216:219], v[136:139], v[112:127]
	global_load_lds_dwordx4 v240, s[98:99]
	s_add_u32 s98, s66, s72
	s_addc_u32 s99, s67, s73
	s_mov_b32 m0, s4
	s_addk_i32 s4, 0x400
	s_waitcnt lgkmcnt(1)
	v_mfma_f32_32x32x16_bf16 v[112:127], v[220:223], v[140:143], v[112:127]
	global_load_lds_dwordx4 v241, s[98:99]
	s_mov_b32 m0, s4
	s_waitcnt lgkmcnt(0)
	v_mfma_f32_32x32x16_bf16 v[112:127], v[224:227], v[144:147], v[112:127]
	global_load_lds_dwordx4 v242, s[98:99]
	s_and_b32 s7, s95, 3
	s_lshl_b32 s7, s7, 14
	v_add_u32_e32 v243, s7, v7
	v_add_u32_e32 v244, s7, v9
	v_add_u32_e32 v245, s7, v10
	v_add_u32_e32 v246, s7, v11
	ds_read_b64_tr_b16 v[188:189], v243 offset:49152
	ds_read_b64_tr_b16 v[190:191], v243 offset:51200
	ds_read_b64_tr_b16 v[192:193], v244
	ds_read_b64_tr_b16 v[194:195], v244 offset:2048
	ds_read_b64_tr_b16 v[196:197], v245
	ds_read_b64_tr_b16 v[198:199], v245 offset:2048
	ds_read_b64_tr_b16 v[200:201], v246
	ds_read_b64_tr_b16 v[202:203], v246 offset:2048
	v_exp_f32_e32 v228, v96
	v_exp_f32_e32 v229, v97
	v_exp_f32_e32 v230, v98
	v_exp_f32_e32 v231, v99
	v_exp_f32_e32 v232, v100
	v_exp_f32_e32 v233, v101
	v_exp_f32_e32 v234, v102
	v_exp_f32_e32 v187, v103
	v_cvt_pk_bf16_f32 v220, v228, v229
	v_cvt_pk_bf16_f32 v221, v230, v231
	v_cvt_pk_bf16_f32 v222, v232, v233
	v_cvt_pk_bf16_f32 v223, v234, v187
	ds_read_b64_tr_b16 v[204:205], v243 offset:53248
	ds_read_b64_tr_b16 v[206:207], v243 offset:55296
	ds_read_b64_tr_b16 v[208:209], v244 offset:4096
	ds_read_b64_tr_b16 v[210:211], v244 offset:6144
	ds_read_b64_tr_b16 v[212:213], v245 offset:4096
	ds_read_b64_tr_b16 v[214:215], v245 offset:6144
	ds_read_b64_tr_b16 v[216:217], v246 offset:4096
	ds_read_b64_tr_b16 v[218:219], v246 offset:6144
	s_waitcnt lgkmcnt(14)
	v_mfma_f32_32x32x16_bf16 v[80:95], v[188:191], v[220:223], v[80:95]
	ds_read_b64_tr_b16 v[188:189], v243 offset:57344
	ds_read_b64_tr_b16 v[190:191], v243 offset:59392
	v_exp_f32_e32 v247, v104
	v_exp_f32_e32 v248, v105
	v_add_f32_e32 v153, 0, v228
	v_add_f32_e32 v153, v229, v153
	s_waitcnt lgkmcnt(14)
	v_mfma_f32_32x32x16_bf16 v[64:79], v[192:195], v[220:223], v[64:79]
	ds_read_b64_tr_b16 v[192:193], v244 offset:8192
	ds_read_b64_tr_b16 v[194:195], v244 offset:10240
	v_exp_f32_e32 v249, v106
	v_exp_f32_e32 v250, v107
	v_add_f32_e32 v153, v230, v153
	v_add_f32_e32 v153, v231, v153
	s_waitcnt lgkmcnt(14)
	v_mfma_f32_32x32x16_bf16 v[48:63], v[196:199], v[220:223], v[48:63]
	ds_read_b64_tr_b16 v[196:197], v245 offset:8192
	ds_read_b64_tr_b16 v[198:199], v245 offset:10240
	v_exp_f32_e32 v251, v108
	v_exp_f32_e32 v252, v109
	v_add_f32_e32 v153, v232, v153
	v_add_f32_e32 v153, v233, v153
	s_waitcnt lgkmcnt(14)
	v_mfma_f32_32x32x16_bf16 v[32:47], v[200:203], v[220:223], v[32:47]
	ds_read_b64_tr_b16 v[200:201], v246 offset:8192
	ds_read_b64_tr_b16 v[202:203], v246 offset:10240
	v_exp_f32_e32 v253, v110
	v_exp_f32_e32 v254, v111
	v_cvt_pk_bf16_f32 v224, v247, v248
	v_cvt_pk_bf16_f32 v225, v249, v250
	v_cvt_pk_bf16_f32 v226, v251, v252
	v_cvt_pk_bf16_f32 v227, v253, v254
	v_add_f32_e32 v153, v234, v153
	v_add_f32_e32 v153, v187, v153
	s_waitcnt lgkmcnt(14)
	v_mfma_f32_32x32x16_bf16 v[80:95], v[204:207], v[224:227], v[80:95]
	ds_read_b64_tr_b16 v[204:205], v243 offset:61440
	ds_read_b64_tr_b16 v[206:207], v243 offset:63488
	v_exp_f32_e32 v228, v112
	v_exp_f32_e32 v229, v113
	v_add_f32_e32 v153, v247, v153
	v_add_f32_e32 v153, v248, v153
	s_waitcnt lgkmcnt(14)
	v_mfma_f32_32x32x16_bf16 v[64:79], v[208:211], v[224:227], v[64:79]
	ds_read_b64_tr_b16 v[208:209], v244 offset:12288
	ds_read_b64_tr_b16 v[210:211], v244 offset:14336
	v_exp_f32_e32 v230, v114
	v_exp_f32_e32 v231, v115
	v_add_f32_e32 v153, v249, v153
	v_add_f32_e32 v153, v250, v153
	s_waitcnt lgkmcnt(14)
	v_mfma_f32_32x32x16_bf16 v[48:63], v[212:215], v[224:227], v[48:63]
	ds_read_b64_tr_b16 v[212:213], v245 offset:12288
	ds_read_b64_tr_b16 v[214:215], v245 offset:14336
	v_exp_f32_e32 v232, v116
	v_exp_f32_e32 v233, v117
	v_add_f32_e32 v153, v251, v153
	v_add_f32_e32 v153, v252, v153
	s_waitcnt lgkmcnt(14)
	v_mfma_f32_32x32x16_bf16 v[32:47], v[216:219], v[224:227], v[32:47]
	ds_read_b64_tr_b16 v[216:217], v246 offset:12288
	ds_read_b64_tr_b16 v[218:219], v246 offset:14336
	v_exp_f32_e32 v234, v118
	v_exp_f32_e32 v187, v119
	v_cvt_pk_bf16_f32 v220, v228, v229
	v_cvt_pk_bf16_f32 v221, v230, v231
	v_cvt_pk_bf16_f32 v222, v232, v233
	v_cvt_pk_bf16_f32 v223, v234, v187
	v_add_f32_e32 v153, v253, v153
	v_add_f32_e32 v153, v254, v153
	s_waitcnt lgkmcnt(14)
	v_mfma_f32_32x32x16_bf16 v[80:95], v[188:191], v[220:223], v[80:95]
	v_exp_f32_e32 v247, v120
	v_exp_f32_e32 v248, v121
	v_add_f32_e32 v153, v228, v153
	v_add_f32_e32 v153, v229, v153
	s_waitcnt lgkmcnt(12)
	v_mfma_f32_32x32x16_bf16 v[64:79], v[192:195], v[220:223], v[64:79]
	v_exp_f32_e32 v249, v122
	v_exp_f32_e32 v250, v123
	v_add_f32_e32 v153, v230, v153
	v_add_f32_e32 v153, v231, v153
	s_waitcnt lgkmcnt(10)
	v_mfma_f32_32x32x16_bf16 v[48:63], v[196:199], v[220:223], v[48:63]
	v_exp_f32_e32 v251, v124
	v_exp_f32_e32 v252, v125
	v_add_f32_e32 v153, v232, v153
	v_add_f32_e32 v153, v233, v153
	s_waitcnt lgkmcnt(8)
	v_mfma_f32_32x32x16_bf16 v[32:47], v[200:203], v[220:223], v[32:47]
	v_exp_f32_e32 v253, v126
	v_exp_f32_e32 v254, v127
	v_cvt_pk_bf16_f32 v224, v247, v248
	v_cvt_pk_bf16_f32 v225, v249, v250
	v_cvt_pk_bf16_f32 v226, v251, v252
	v_cvt_pk_bf16_f32 v227, v253, v254
	v_add_f32_e32 v153, v234, v153
	v_add_f32_e32 v153, v187, v153
	s_waitcnt lgkmcnt(6)
	v_mfma_f32_32x32x16_bf16 v[80:95], v[204:207], v[224:227], v[80:95]
	v_add_f32_e32 v153, v247, v153
	v_add_f32_e32 v153, v248, v153
	s_waitcnt lgkmcnt(4)
	v_mfma_f32_32x32x16_bf16 v[64:79], v[208:211], v[224:227], v[64:79]
	v_add_f32_e32 v153, v249, v153
	v_add_f32_e32 v153, v250, v153
	s_waitcnt lgkmcnt(2)
	v_mfma_f32_32x32x16_bf16 v[48:63], v[212:215], v[224:227], v[48:63]
	v_add_f32_e32 v153, v251, v153
	v_add_f32_e32 v153, v252, v153
	s_waitcnt lgkmcnt(0)
	v_mfma_f32_32x32x16_bf16 v[32:47], v[216:219], v[224:227], v[32:47]
	v_add_f32_e32 v153, v253, v153
	v_add_f32_e32 v153, v254, v153
	v_add_f32_e32 v6, v6, v153
	s_add_u32 s72, s72, 0x20000
	s_addc_u32 s73, s73, 0
	s_add_i32 s95, s95, 1
	s_mov_b32 s71, s8
	s_mov_b32 s8, s78
	s_mov_b32 s78, s88
	s_mov_b32 s88, s71
	s_sub_i32 s101, s101, 1
	s_cmp_lg_u32 s101, 0
	s_waitcnt vmcnt(4) lgkmcnt(0)
	s_barrier
	s_cbranch_scc1 .Latt_flA_top
	s_lshl_b32 s4, s100, 6
	s_sub_i32 s33, s33, s4
	s_sub_i32 s93, s93, s4
	s_sub_u32 s90, s90, s4
	s_subb_u32 s91, s91, 0
	v_add_u32_e32 v179, s4, v179
	s_branch .Latt_slow

.LBB0_1402:
	s_ashr_i32 s17, s16, 31
	s_lshl_b64 s[18:19], s[16:17], 19
	s_add_u32 s18, s76, s18
	s_addc_u32 s19, s78, s19
	s_and_b64 s[20:21], s[6:7], exec
	s_cselect_b32 s17, s19, s1
	s_cselect_b32 s33, s18, s0
	s_ashr_i32 s15, s14, 31
	s_lshl_b64 s[20:21], s[14:15], 19
	s_add_u32 s20, s31, s20
	s_addc_u32 s21, s34, s21
	s_and_b64 s[28:29], s[6:7], exec
	s_cselect_b32 s15, s21, s27
	s_cselect_b32 s50, s20, s26
	s_add_u32 s0, s0, 0x40080
	s_addc_u32 s1, s1, 0
	s_add_u32 s51, s26, 0x100
	s_addc_u32 s52, s27, 0
	s_mov_b32 s53, -2
	s_waitcnt lgkmcnt(0)
	v_mov_b64_e32 v[0:1], 0
	v_mov_b64_e32 v[2:3], 0
	v_mov_b64_e32 v[4:5], 0
	v_mov_b64_e32 v[6:7], 0
	v_mov_b64_e32 v[8:9], 0
	v_mov_b64_e32 v[10:11], 0
	v_mov_b64_e32 v[12:13], 0
	v_mov_b64_e32 v[14:15], 0
	v_mov_b64_e32 v[16:17], 0
	v_mov_b64_e32 v[18:19], 0
	v_mov_b64_e32 v[20:21], 0
	v_mov_b64_e32 v[22:23], 0
	v_mov_b64_e32 v[24:25], 0
	v_mov_b64_e32 v[26:27], 0
	v_mov_b64_e32 v[28:29], 0
	v_mov_b64_e32 v[30:31], 0
	v_mov_b64_e32 v[32:33], 0
	v_mov_b64_e32 v[34:35], 0
	v_mov_b64_e32 v[36:37], 0
	v_mov_b64_e32 v[38:39], 0
	v_mov_b64_e32 v[40:41], 0
	v_mov_b64_e32 v[42:43], 0
	v_mov_b64_e32 v[44:45], 0
	v_mov_b64_e32 v[46:47], 0
	v_mov_b64_e32 v[48:49], 0
	v_mov_b64_e32 v[50:51], 0
	v_mov_b64_e32 v[52:53], 0
	v_mov_b64_e32 v[54:55], 0
	v_mov_b64_e32 v[56:57], 0
	v_mov_b64_e32 v[58:59], 0
	v_mov_b64_e32 v[60:61], 0
	v_mov_b64_e32 v[62:63], 0
	v_mov_b64_e32 v[64:65], 0
	v_mov_b64_e32 v[66:67], 0
	v_mov_b64_e32 v[68:69], 0
	v_mov_b64_e32 v[70:71], 0
	v_mov_b64_e32 v[72:73], 0
	v_mov_b64_e32 v[74:75], 0
	v_mov_b64_e32 v[76:77], 0
	v_mov_b64_e32 v[78:79], 0
	v_mov_b64_e32 v[80:81], 0
	v_mov_b64_e32 v[82:83], 0
	v_mov_b64_e32 v[84:85], 0
	v_mov_b64_e32 v[86:87], 0
	v_mov_b64_e32 v[88:89], 0
	v_mov_b64_e32 v[90:91], 0
	v_mov_b64_e32 v[92:93], 0
	v_mov_b64_e32 v[94:95], 0
	v_mov_b64_e32 v[96:97], 0
	v_mov_b64_e32 v[98:99], 0
	v_mov_b64_e32 v[100:101], 0
	v_mov_b64_e32 v[102:103], 0
	v_mov_b64_e32 v[104:105], 0
	v_mov_b64_e32 v[106:107], 0
	v_mov_b64_e32 v[108:109], 0
	v_mov_b64_e32 v[110:111], 0
	v_mov_b64_e32 v[112:113], 0
	v_mov_b64_e32 v[114:115], 0
	v_mov_b64_e32 v[116:117], 0
	v_mov_b64_e32 v[118:119], 0
	v_mov_b64_e32 v[120:121], 0
	v_mov_b64_e32 v[122:123], 0
	v_mov_b64_e32 v[124:125], 0
	v_mov_b64_e32 v[126:127], 0

.LBB0_1487:
	s_ashr_i32 s15, s14, 31
	s_lshl_b64 s[16:17], s[14:15], 19
	s_add_u32 s16, s66, s16
	s_addc_u32 s17, s67, s17
	s_and_b64 s[18:19], s[4:5], exec
	s_cselect_b32 s15, s17, s1
	s_cselect_b32 s41, s16, s0
	s_ashr_i32 s13, s12, 31
	s_lshl_b64 s[18:19], s[12:13], 19
	s_add_u32 s18, s26, s18
	s_addc_u32 s19, s27, s19
	s_and_b64 s[24:25], s[4:5], exec
	s_cselect_b32 s13, s19, s23
	s_cselect_b32 s42, s18, s22
	s_add_u32 s0, s0, 0x40080
	s_addc_u32 s1, s1, 0
	s_add_u32 s43, s22, 0x100
	s_addc_u32 s44, s23, 0
	s_mov_b32 s45, -2
	v_mov_b64_e32 v[0:1], 0
	v_mov_b64_e32 v[2:3], 0
	v_mov_b64_e32 v[4:5], 0
	v_mov_b64_e32 v[6:7], 0
	v_mov_b64_e32 v[8:9], 0
	v_mov_b64_e32 v[10:11], 0
	v_mov_b64_e32 v[12:13], 0
	v_mov_b64_e32 v[14:15], 0
	v_mov_b64_e32 v[16:17], 0
	v_mov_b64_e32 v[18:19], 0
	v_mov_b64_e32 v[20:21], 0
	v_mov_b64_e32 v[22:23], 0
	v_mov_b64_e32 v[24:25], 0
	v_mov_b64_e32 v[26:27], 0
	v_mov_b64_e32 v[28:29], 0
	v_mov_b64_e32 v[30:31], 0
	v_mov_b64_e32 v[32:33], 0
	v_mov_b64_e32 v[34:35], 0
	v_mov_b64_e32 v[36:37], 0
	v_mov_b64_e32 v[38:39], 0
	v_mov_b64_e32 v[40:41], 0
	v_mov_b64_e32 v[42:43], 0
	v_mov_b64_e32 v[44:45], 0
	v_mov_b64_e32 v[46:47], 0
	v_mov_b64_e32 v[48:49], 0
	v_mov_b64_e32 v[50:51], 0
	v_mov_b64_e32 v[52:53], 0
	v_mov_b64_e32 v[54:55], 0
	v_mov_b64_e32 v[56:57], 0
	v_mov_b64_e32 v[58:59], 0
	v_mov_b64_e32 v[60:61], 0
	v_mov_b64_e32 v[62:63], 0
	v_mov_b64_e32 v[64:65], 0
	v_mov_b64_e32 v[66:67], 0
	v_mov_b64_e32 v[68:69], 0
	v_mov_b64_e32 v[70:71], 0
	v_mov_b64_e32 v[72:73], 0
	v_mov_b64_e32 v[74:75], 0
	v_mov_b64_e32 v[76:77], 0
	v_mov_b64_e32 v[78:79], 0
	v_mov_b64_e32 v[80:81], 0
	v_mov_b64_e32 v[82:83], 0
	v_mov_b64_e32 v[84:85], 0
	v_mov_b64_e32 v[86:87], 0
	v_mov_b64_e32 v[88:89], 0
	v_mov_b64_e32 v[90:91], 0
	v_mov_b64_e32 v[92:93], 0
	v_mov_b64_e32 v[94:95], 0
	v_mov_b64_e32 v[96:97], 0
	v_mov_b64_e32 v[98:99], 0
	v_mov_b64_e32 v[100:101], 0
	v_mov_b64_e32 v[102:103], 0
	v_mov_b64_e32 v[104:105], 0
	v_mov_b64_e32 v[106:107], 0
	v_mov_b64_e32 v[108:109], 0
	v_mov_b64_e32 v[110:111], 0
	v_mov_b64_e32 v[112:113], 0
	v_mov_b64_e32 v[114:115], 0
	v_mov_b64_e32 v[116:117], 0
	v_mov_b64_e32 v[118:119], 0
	v_mov_b64_e32 v[120:121], 0
	v_mov_b64_e32 v[122:123], 0
	v_mov_b64_e32 v[124:125], 0
	v_mov_b64_e32 v[126:127], 0

.LBB0_1562:
	s_ashr_i32 s17, s16, 31
	s_lshl_b64 s[18:19], s[16:17], 21
	s_add_u32 s18, s68, s18
	s_addc_u32 s19, s69, s19
	s_and_b64 s[20:21], s[4:5], exec
	s_cselect_b32 s17, s19, s1
	s_cselect_b32 s33, s18, s0
	s_ashr_i32 s15, s14, 31
	s_lshl_b64 s[20:21], s[14:15], 21
	s_add_u32 s20, s30, s20
	s_addc_u32 s21, s31, s21
	s_and_b64 s[28:29], s[4:5], exec
	s_cselect_b32 s15, s21, s27
	s_cselect_b32 s49, s20, s26
	s_add_u32 s0, s0, 0x100080
	s_addc_u32 s1, s1, 0
	s_add_u32 s50, s26, 0x100
	s_addc_u32 s51, s27, 0
	s_mov_b32 s52, -2
	s_waitcnt lgkmcnt(0)
	v_mov_b64_e32 v[0:1], 0
	v_mov_b64_e32 v[2:3], 0
	v_mov_b64_e32 v[4:5], 0
	v_mov_b64_e32 v[6:7], 0
	v_mov_b64_e32 v[8:9], 0
	v_mov_b64_e32 v[10:11], 0
	v_mov_b64_e32 v[12:13], 0
	v_mov_b64_e32 v[14:15], 0
	v_mov_b64_e32 v[16:17], 0
	v_mov_b64_e32 v[18:19], 0
	v_mov_b64_e32 v[20:21], 0
	v_mov_b64_e32 v[22:23], 0
	v_mov_b64_e32 v[24:25], 0
	v_mov_b64_e32 v[26:27], 0
	v_mov_b64_e32 v[28:29], 0
	v_mov_b64_e32 v[30:31], 0
	v_mov_b64_e32 v[32:33], 0
	v_mov_b64_e32 v[34:35], 0
	v_mov_b64_e32 v[36:37], 0
	v_mov_b64_e32 v[38:39], 0
	v_mov_b64_e32 v[40:41], 0
	v_mov_b64_e32 v[42:43], 0
	v_mov_b64_e32 v[44:45], 0
	v_mov_b64_e32 v[46:47], 0
	v_mov_b64_e32 v[48:49], 0
	v_mov_b64_e32 v[50:51], 0
	v_mov_b64_e32 v[52:53], 0
	v_mov_b64_e32 v[54:55], 0
	v_mov_b64_e32 v[56:57], 0
	v_mov_b64_e32 v[58:59], 0
	v_mov_b64_e32 v[60:61], 0
	v_mov_b64_e32 v[62:63], 0
	v_mov_b64_e32 v[64:65], 0
	v_mov_b64_e32 v[66:67], 0
	v_mov_b64_e32 v[68:69], 0
	v_mov_b64_e32 v[70:71], 0
	v_mov_b64_e32 v[72:73], 0
	v_mov_b64_e32 v[74:75], 0
	v_mov_b64_e32 v[76:77], 0
	v_mov_b64_e32 v[78:79], 0
	v_mov_b64_e32 v[80:81], 0
	v_mov_b64_e32 v[82:83], 0
	v_mov_b64_e32 v[84:85], 0
	v_mov_b64_e32 v[86:87], 0
	v_mov_b64_e32 v[88:89], 0
	v_mov_b64_e32 v[90:91], 0
	v_mov_b64_e32 v[92:93], 0
	v_mov_b64_e32 v[94:95], 0
	v_mov_b64_e32 v[96:97], 0
	v_mov_b64_e32 v[98:99], 0
	v_mov_b64_e32 v[100:101], 0
	v_mov_b64_e32 v[102:103], 0
	v_mov_b64_e32 v[104:105], 0
	v_mov_b64_e32 v[106:107], 0
	v_mov_b64_e32 v[108:109], 0
	v_mov_b64_e32 v[110:111], 0
	v_mov_b64_e32 v[112:113], 0
	v_mov_b64_e32 v[114:115], 0
	v_mov_b64_e32 v[116:117], 0
	v_mov_b64_e32 v[118:119], 0
	v_mov_b64_e32 v[120:121], 0
	v_mov_b64_e32 v[122:123], 0
	v_mov_b64_e32 v[124:125], 0
	v_mov_b64_e32 v[126:127], 0

	.amdhsa_kernel _Z8yoco_fwd4Args
		.amdhsa_group_segment_fixed_size 0
		.amdhsa_private_segment_fixed_size 0
		.amdhsa_kernarg_size 536
		.amdhsa_user_sgpr_count 2
		.amdhsa_user_sgpr_dispatch_ptr 0
		.amdhsa_user_sgpr_queue_ptr 0
		.amdhsa_user_sgpr_kernarg_segment_ptr 1
		.amdhsa_user_sgpr_dispatch_id 0
		.amdhsa_user_sgpr_kernarg_preload_length 0
		.amdhsa_user_sgpr_kernarg_preload_offset 0
		.amdhsa_user_sgpr_private_segment_size 0
		.amdhsa_uses_dynamic_stack 0
		.amdhsa_enable_private_segment 0
		.amdhsa_system_sgpr_workgroup_id_x 1
		.amdhsa_system_sgpr_workgroup_id_y 0
		.amdhsa_system_sgpr_workgroup_id_z 0
		.amdhsa_system_sgpr_workgroup_info 0
		.amdhsa_system_vgpr_workitem_id 2
		.amdhsa_next_free_vgpr 255
		.amdhsa_next_free_sgpr 102
		.amdhsa_accum_offset 256
		.amdhsa_reserve_vcc 1
		.amdhsa_float_round_mode_32 0
		.amdhsa_float_round_mode_16_64 0
		.amdhsa_float_denorm_mode_32 3
		.amdhsa_float_denorm_mode_16_64 3
		.amdhsa_dx10_clamp 1
		.amdhsa_ieee_mode 1
		.amdhsa_fp16_overflow 0
		.amdhsa_tg_split 0
		.amdhsa_exception_fp_ieee_invalid_op 0
		.amdhsa_exception_fp_denorm_src 0
		.amdhsa_exception_fp_ieee_div_zero 0
		.amdhsa_exception_fp_ieee_overflow 0
		.amdhsa_exception_fp_ieee_underflow 0
		.amdhsa_exception_fp_ieee_inexact 0
		.amdhsa_exception_int_div_zero 0
	.end_amdhsa_kernel

amdhsa.kernels:
  - .agpr_count:     0
    .args:
      - .offset:         0
        .size:           280
        .value_kind:     by_value
      - .offset:         280
        .size:           4
        .value_kind:     hidden_block_count_x
      - .offset:         284
        .size:           4
        .value_kind:     hidden_block_count_y
      - .offset:         288
        .size:           4
        .value_kind:     hidden_block_count_z
      - .offset:         292
        .size:           2
        .value_kind:     hidden_group_size_x
      - .offset:         294
        .size:           2
        .value_kind:     hidden_group_size_y
      - .offset:         296
        .size:           2
        .value_kind:     hidden_group_size_z
      - .offset:         298
        .size:           2
        .value_kind:     hidden_remainder_x
      - .offset:         300
        .size:           2
        .value_kind:     hidden_remainder_y
      - .offset:         302
        .size:           2
        .value_kind:     hidden_remainder_z
      - .offset:         320
        .size:           8
        .value_kind:     hidden_global_offset_x
      - .offset:         328
        .size:           8
        .value_kind:     hidden_global_offset_y
      - .offset:         336
        .size:           8
        .value_kind:     hidden_global_offset_z
      - .offset:         344
        .size:           2
        .value_kind:     hidden_grid_dims
      - .offset:         368
        .size:           8
        .value_kind:     hidden_multigrid_sync_arg
      - .offset:         400
        .size:           4
        .value_kind:     hidden_dynamic_lds_size
    .group_segment_fixed_size: 0
    .kernarg_segment_align: 8
    .kernarg_segment_size: 536
    .language:       OpenCL C
    .language_version:
      - 2
      - 0
    .max_flat_workgroup_size: 512
    .name:           _Z8yoco_fwd4Args
    .private_segment_fixed_size: 0
    .sgpr_count:     108
    .sgpr_spill_count: 55
    .symbol:         _Z8yoco_fwd4Args.kd
    .uniform_work_group_size: 1
    .uses_dynamic_stack: false
    .vgpr_count:     255
    .vgpr_spill_count: 0
    .wavefront_size: 64
